# skinny_stage_att: second item's loads issued before the first item's arithmetic (16 loads in flight per round trip)
# baseline (speedup 1.0000x reference)
; #define LAS __attribute__((address_space(3)))
; __device__ __forceinline__ u32x4 pack8(const f32x4& a, const f32x4& b) { u32x4 w; w.x = pk2(a[0], a[1]); w.y = pk2(a[2], a[3]); w.z = pk2(b[0], b[1]); w.w = pk2(b[2], b[3]); return w; }
; __device__ __forceinline__ void skinny_stage_att(Frame& F) {
;     ...
;     for (int i = F.tid; i < 32 * 128; i += NT) { const int r = i >> 7, c = i & 127, head = c >> 3, d0 = (c & 7) * 8, row = MPT + r;
;         const int unit = (r >> 2) * 16 + (head >> 2) * 4 + (r & 3);
;         const float* sp = so + (size_t)unit * 768 + (head & 3) * 64 + d0; const float* gt = gate + (size_t)row * 64 + head * 3;
;         const float g0 = gt[0], g1 = gt[1], g2 = gt[2];
;         float zf[8]; unpack8(*(const u32x4*)(P + (size_t)row * NPROJ + C_AZ + head * 64 + d0), zf);
;         f32x4 o[2];
; #pragma unroll
;         for (int h = 0; h < 2; ++h) { const f32x4 a = *(const f32x4*)(sp + 4 * h), b = *(const f32x4*)(sp + 256 + 4 * h), w = *(const f32x4*)(sp + 512 + 4 * h);
; #pragma unroll
;             for (int j = 0; j < 4; ++j) o[h][j] = (g0 * a[j] + g1 * b[j] + g2 * w[j]) * zf[4 * h + j]; }
;         *(LAS u32x4*)(F.lds + r * (1024 * 2 + 16) + c * 16) = pack8(o[0], o[1]); }
.LBB0_1329:
	v_ashrrev_i32_e32 v29, 7, v6
	v_ashrrev_i32_e32 v3, 5, v6
	v_lshrrev_b32_e32 v4, 3, v6
	v_and_b32_e32 v3, -16, v3
	v_and_b32_e32 v33, 12, v4
	v_and_b32_e32 v4, 3, v29
	v_and_b32_e32 v31, 56, v7
	v_add_u32_e32 v2, 0x2000, v29
	v_or3_b32 v3, v3, v33, v4
	v_mad_i64_i32 v[4:5], s[22:23], v3, s56, v[10:11]
	v_lshlrev_b32_e32 v98, 2, v31
	v_ashrrev_i32_e32 v3, 31, v2
	v_lshl_add_u64 v[8:9], v[4:5], 0, v[98:99]
	v_lshlrev_b64 v[4:5], 8, v[2:3]
	v_lshl_add_u64 v[4:5], v[12:13], 0, v[4:5]
	global_load_dwordx3 v[72:74], v[4:5], off
	v_mov_b64_e32 v[4:5], s[18:19]
	v_mad_i64_i32 v[2:3], s[22:23], v2, s87, v[4:5]
	v_mov_b32_e32 v27, v99
	v_lshl_add_u64 v[34:35], v[2:3], 0, v[26:27]
	v_lshlrev_b32_e32 v2, 1, v31
	v_mov_b32_e32 v3, v99
	v_lshl_add_u64 v[34:35], v[34:35], 0, v[2:3]
	v_add_co_u32_e32 v34, vcc, s57, v34
	v_add_u32_e32 v7, 0x2000, v7
	s_nop 0
	v_addc_co_u32_e32 v35, vcc, 0, v35, vcc
	global_load_dwordx4 v[44:47], v[34:35], off offset:1024
	global_load_dwordx4 v[48:51], v[8:9], off offset:16
	global_load_dwordx4 v[52:55], v[8:9], off
	global_load_dwordx4 v[56:59], v[8:9], off offset:1040
	global_load_dwordx4 v[60:63], v[8:9], off offset:1024
	global_load_dwordx4 v[64:67], v[8:9], off offset:2064
	global_load_dwordx4 v[68:71], v[8:9], off offset:2048
	v_add_u32_e32 v140, 0x200, v6
	v_ashrrev_i32_e32 v141, 7, v140
	v_ashrrev_i32_e32 v140, 5, v140
	v_and_b32_e32 v140, -16, v140
	v_and_b32_e32 v142, 3, v141
	v_add_u32_e32 v144, 0x2000, v141
	v_or3_b32 v140, v140, v33, v142
	v_mad_i64_i32 v[146:147], s[22:23], v140, s56, v[10:11]
	v_ashrrev_i32_e32 v145, 31, v144
	v_mov_b64_e32 v[148:149], s[18:19]
	v_mad_i64_i32 v[148:149], s[22:23], v144, s87, v[148:149]
	v_lshlrev_b64 v[150:151], 8, v[144:145]
	v_lshl_add_u64 v[148:149], v[148:149], 0, v[26:27]
	v_lshl_add_u64 v[150:151], v[12:13], 0, v[150:151]
	v_lshl_add_u64 v[148:149], v[148:149], 0, v[2:3]
	global_load_dwordx3 v[100:102], v[150:151], off
	v_add_co_u32_e32 v148, vcc, s57, v148
	v_lshl_add_u64 v[146:147], v[146:147], 0, v[98:99]
	s_nop 0
	v_addc_co_u32_e32 v149, vcc, 0, v149, vcc
	global_load_dwordx4 v[104:107], v[148:149], off offset:1024
	global_load_dwordx4 v[108:111], v[146:147], off offset:16
	global_load_dwordx4 v[112:115], v[146:147], off
	global_load_dwordx4 v[116:119], v[146:147], off offset:1040
	global_load_dwordx4 v[120:123], v[146:147], off offset:1024
	global_load_dwordx4 v[124:127], v[146:147], off offset:2064
	global_load_dwordx4 v[128:131], v[146:147], off offset:2048
	s_waitcnt vmcnt(14)
	v_lshlrev_b32_e32 v8, 16, v44
	v_and_b32_e32 v9, 0xffff0000, v44
	v_mov_b32_e32 v44, v74
	s_waitcnt vmcnt(10)
	v_pk_mul_f32 v[34:35], v[72:73], v[60:61] op_sel:[1,0]
	s_nop 0
	v_pk_fma_f32 v[34:35], v[72:73], v[52:53], v[34:35] op_sel_hi:[0,1,1]
	v_pk_mul_f32 v[52:53], v[72:73], v[62:63] op_sel:[1,0]
	s_waitcnt vmcnt(8)
	v_pk_fma_f32 v[34:35], v[44:45], v[68:69], v[34:35] op_sel_hi:[0,1,1]
	v_pk_fma_f32 v[52:53], v[72:73], v[54:55], v[52:53] op_sel_hi:[0,1,1]
	v_pk_mul_f32 v[54:55], v[72:73], v[56:57] op_sel:[1,0]
	v_pk_mul_f32 v[8:9], v[34:35], v[8:9]
	v_lshlrev_b32_e32 v34, 16, v45
	v_and_b32_e32 v35, 0xffff0000, v45
	v_pk_fma_f32 v[52:53], v[44:45], v[70:71], v[52:53] op_sel_hi:[0,1,1]
	v_pk_fma_f32 v[48:49], v[72:73], v[48:49], v[54:55] op_sel_hi:[0,1,1]
	v_pk_mul_f32 v[34:35], v[52:53], v[34:35]
	v_lshlrev_b32_e32 v52, 16, v46
	v_and_b32_e32 v53, 0xffff0000, v46
	v_pk_fma_f32 v[48:49], v[44:45], v[64:65], v[48:49] op_sel_hi:[0,1,1]
	v_pk_mul_f32 v[48:49], v[48:49], v[52:53]
	v_pk_mul_f32 v[52:53], v[72:73], v[58:59] op_sel:[1,0]
	v_lshlrev_b32_e32 v46, 16, v47
	v_pk_fma_f32 v[50:51], v[72:73], v[50:51], v[52:53] op_sel_hi:[0,1,1]
	v_and_b32_e32 v47, 0xffff0000, v47
	v_pk_fma_f32 v[44:45], v[44:45], v[66:67], v[50:51] op_sel_hi:[0,1,1]
	v_pk_mul_f32 v[50:51], v[44:45], v[46:47]
	v_cvt_pk_bf16_f32 v44, v8, v9
	v_mad_u64_u32 v[8:9], s[22:23], v29, s80, v[14:15]
	v_cvt_pk_bf16_f32 v45, v34, v35
	v_cvt_pk_bf16_f32 v46, v48, v49
	v_cvt_pk_bf16_f32 v47, v50, v51
	ds_write_b128 v8, v[44:47]
	s_waitcnt vmcnt(6)
	v_lshlrev_b32_e32 v8, 16, v104
	v_and_b32_e32 v9, 0xffff0000, v104
	v_mov_b32_e32 v104, v102
	s_waitcnt vmcnt(2)
	v_pk_mul_f32 v[34:35], v[100:101], v[120:121] op_sel:[1,0]
	s_nop 0
	v_pk_fma_f32 v[34:35], v[100:101], v[112:113], v[34:35] op_sel_hi:[0,1,1]
	v_pk_mul_f32 v[112:113], v[100:101], v[122:123] op_sel:[1,0]
	s_waitcnt vmcnt(0)
	v_pk_fma_f32 v[34:35], v[104:105], v[128:129], v[34:35] op_sel_hi:[0,1,1]
	v_pk_fma_f32 v[112:113], v[100:101], v[114:115], v[112:113] op_sel_hi:[0,1,1]
	v_pk_mul_f32 v[114:115], v[100:101], v[116:117] op_sel:[1,0]
	v_pk_mul_f32 v[8:9], v[34:35], v[8:9]
	v_lshlrev_b32_e32 v34, 16, v105
	v_and_b32_e32 v35, 0xffff0000, v105
	v_pk_fma_f32 v[112:113], v[104:105], v[130:131], v[112:113] op_sel_hi:[0,1,1]
	v_pk_fma_f32 v[108:109], v[100:101], v[108:109], v[114:115] op_sel_hi:[0,1,1]
	v_pk_mul_f32 v[34:35], v[112:113], v[34:35]
	v_lshlrev_b32_e32 v112, 16, v106
	v_and_b32_e32 v113, 0xffff0000, v106
	v_pk_fma_f32 v[108:109], v[104:105], v[124:125], v[108:109] op_sel_hi:[0,1,1]
	v_pk_mul_f32 v[108:109], v[108:109], v[112:113]
	v_pk_mul_f32 v[112:113], v[100:101], v[118:119] op_sel:[1,0]
	v_lshlrev_b32_e32 v106, 16, v107
	v_pk_fma_f32 v[110:111], v[100:101], v[110:111], v[112:113] op_sel_hi:[0,1,1]
	v_and_b32_e32 v107, 0xffff0000, v107
	v_pk_fma_f32 v[104:105], v[104:105], v[126:127], v[110:111] op_sel_hi:[0,1,1]
	v_pk_mul_f32 v[110:111], v[104:105], v[106:107]
	v_cvt_pk_bf16_f32 v104, v8, v9
	v_mad_u64_u32 v[8:9], s[22:23], v141, s80, v[14:15]
	s_movk_i32 s22, 0xbff
	s_nop 0
	v_cmp_lt_i32_e32 vcc, s22, v6
	v_cvt_pk_bf16_f32 v105, v34, v35
	v_cvt_pk_bf16_f32 v106, v108, v109
	v_cvt_pk_bf16_f32 v107, v110, v111
	v_add_u32_e32 v6, 0x400, v6
	s_or_b64 s[54:55], vcc, s[54:55]
	ds_write_b128 v8, v[104:107]
	s_andn2_b64 exec, exec, s[54:55]
	s_cbranch_execnz .LBB0_1329
